# speedup vs baseline: 1.0107x; 1.0098x over previous
; #define WAIT_V(n) asm volatile("s_waitcnt vmcnt(" #n ")" ::: "memory")
; #define BAR __builtin_amdgcn_s_barrier()
; __device__ __forceinline__ void gemm_run(const Params& p, const u16* A1, const u16* Bt1, int M1, int N1, int K, int mode1,
;                                          const float* resid, u16* shm, const u16* A2, const u16* Bt2, int M2, int N2,
;                                          int mode2) {
;     ...
;     f32x4 acc[2][2][4][2] = {};
;     bf16x8 At[4][2], B0[2][2], B1[2][2];
;     STAGE(SB(0, 0), Bt, bcol, 0); STAGE(SA(0, 0), A, brow, 0);
;     STAGE(SB(0, 1), Bt, bcol + HALF, 0); STAGE(SA(0, 1), A, brow + HALF, 0);
;     if (wr == 1) BAR;
;     WAIT_V(4); BAR;
;     STAGE(SB(1, 0), Bt, bcol, 1); STAGE(SA(1, 0), A, brow, 1); STAGE(SB(1, 1), Bt, bcol + HALF, 1);
;     WAIT_V(6); BAR;
.LBB0_396:
	s_ashr_i32 s76, s91, 31
	s_mul_hi_u32 s0, s91, s96
	s_mul_i32 s2, s76, s96
	s_add_i32 s1, s0, s2
	s_mul_i32 s0, s91, s96
	s_lshl_b64 s[0:1], s[0:1], 1
	s_add_u32 s10, s56, s0
	s_addc_u32 s11, s57, s1
	s_mov_b32 s0, m0
	s_mov_b32 m0, s67
	s_nop 0
	global_load_lds_dwordx4 v135, s[10:11]
	s_mov_b32 m0, s0
	s_ashr_i32 s77, s74, 31
	s_mov_b32 s0, m0
	s_mov_b32 m0, s68
	s_nop 0
	global_load_lds_dwordx4 v182, s[10:11]
	s_mov_b32 m0, s0
	s_mul_hi_u32 s0, s74, s96
	s_mul_i32 s3, s77, s96
	s_add_i32 s1, s0, s3
	s_mul_i32 s0, s74, s96
	s_lshl_b64 s[0:1], s[0:1], 1
	s_add_u32 s12, s14, s0
	s_addc_u32 s13, s15, s1
	s_mov_b32 s0, m0
	s_mov_b32 m0, s65
	s_nop 0
	global_load_lds_dwordx4 v135, s[12:13]
	s_mov_b32 m0, s0
	s_nop 0
	s_mov_b32 s0, m0
	s_mov_b32 m0, s69
	s_nop 0
	global_load_lds_dwordx4 v182, s[12:13]
	s_mov_b32 m0, s0
	s_or_b32 s0, s91, 0x80
	s_mul_hi_u32 s1, s0, s96
	s_add_i32 s1, s1, s2
	s_mul_i32 s0, s0, s96
	s_lshl_b64 s[0:1], s[0:1], 1
	s_add_u32 s0, s56, s0
	s_addc_u32 s1, s57, s1
	s_mov_b32 s2, m0
	s_mov_b32 m0, s70
	s_nop 0
	global_load_lds_dwordx4 v135, s[0:1]
	s_mov_b32 m0, s2
	s_nop 0
	s_mov_b32 s2, m0
	s_mov_b32 m0, s71
	s_nop 0
	global_load_lds_dwordx4 v182, s[0:1]
	s_mov_b32 m0, s2
	s_or_b32 s2, s74, 0x80
	s_mul_hi_u32 s8, s2, s96
	s_add_i32 s3, s8, s3
	s_mul_i32 s2, s2, s96
	s_lshl_b64 s[2:3], s[2:3], 1
	s_add_u32 s8, s14, s2
	s_addc_u32 s9, s15, s3
	s_mov_b32 s2, m0
	s_mov_b32 m0, s72
	s_nop 0
	global_load_lds_dwordx4 v135, s[8:9]
	s_mov_b32 m0, s2
	s_nop 0
	s_mov_b32 s2, m0
	s_mov_b32 m0, s73
	s_nop 0
	global_load_lds_dwordx4 v182, s[8:9]
	s_mov_b32 m0, s2
	v_mov_b32_e32 v125, 0
	v_mov_b32_e32 v2, v125
	v_mov_b32_e32 v3, v125
	v_mov_b32_e32 v4, v125
	v_mov_b32_e32 v5, v125
	v_mov_b32_e32 v6, v125
	v_mov_b32_e32 v7, v125
	v_mov_b32_e32 v8, v125
	v_mov_b32_e32 v9, v125
	v_mov_b32_e32 v10, v125
	v_mov_b32_e32 v11, v125
	v_mov_b32_e32 v12, v125
	v_mov_b32_e32 v13, v125
	v_mov_b32_e32 v14, v125
	v_mov_b32_e32 v15, v125
	v_mov_b32_e32 v16, v125
	v_mov_b32_e32 v17, v125
	v_mov_b32_e32 v18, v125
	v_mov_b32_e32 v19, v125
	v_mov_b32_e32 v20, v125
	v_mov_b32_e32 v21, v125
	v_mov_b32_e32 v22, v125
	v_mov_b32_e32 v23, v125
	v_mov_b32_e32 v24, v125
	v_mov_b32_e32 v25, v125
	v_mov_b32_e32 v26, v125
	v_mov_b32_e32 v27, v125
	v_mov_b32_e32 v28, v125
	v_mov_b32_e32 v29, v125
	v_mov_b32_e32 v30, v125
	v_mov_b32_e32 v31, v125
	v_mov_b32_e32 v32, v125
	v_mov_b32_e32 v33, v125
	v_mov_b32_e32 v34, v125
	v_mov_b32_e32 v35, v125
	v_mov_b32_e32 v36, v125
	v_mov_b32_e32 v37, v125
	v_mov_b32_e32 v38, v125
	v_mov_b32_e32 v39, v125
	v_mov_b32_e32 v40, v125
	v_mov_b32_e32 v41, v125
	v_mov_b32_e32 v42, v125
	v_mov_b32_e32 v43, v125
	v_mov_b32_e32 v44, v125
	v_mov_b32_e32 v45, v125
	v_mov_b32_e32 v46, v125
	v_mov_b32_e32 v47, v125
	v_mov_b32_e32 v48, v125
	v_mov_b32_e32 v49, v125
	v_mov_b32_e32 v50, v125
	v_mov_b32_e32 v51, v125
	v_mov_b32_e32 v52, v125
	v_mov_b32_e32 v53, v125
	v_mov_b32_e32 v54, v125
	v_mov_b32_e32 v55, v125
	v_mov_b32_e32 v56, v125
	v_mov_b32_e32 v57, v125
	v_mov_b32_e32 v58, v125
	v_mov_b32_e32 v59, v125
	v_mov_b32_e32 v60, v125
	v_mov_b32_e32 v61, v125
	v_mov_b32_e32 v62, v125
	v_mov_b32_e32 v63, v125
	v_mov_b32_e32 v64, v125
	v_mov_b32_e32 v65, v125
	v_mov_b32_e32 v66, v125
	v_mov_b32_e32 v67, v125
	v_mov_b32_e32 v68, v125
	v_mov_b32_e32 v69, v125
	v_mov_b32_e32 v70, v125
	v_mov_b32_e32 v71, v125
	v_mov_b32_e32 v72, v125
	v_mov_b32_e32 v73, v125
	v_mov_b32_e32 v74, v125
	v_mov_b32_e32 v75, v125
	v_mov_b32_e32 v76, v125
	v_mov_b32_e32 v77, v125
	v_mov_b32_e32 v78, v125
	v_mov_b32_e32 v79, v125
	v_mov_b32_e32 v80, v125
	v_mov_b32_e32 v81, v125
	v_mov_b32_e32 v82, v125
	v_mov_b32_e32 v83, v125
	v_mov_b32_e32 v84, v125
	v_mov_b32_e32 v85, v125
	v_mov_b32_e32 v86, v125
	v_mov_b32_e32 v87, v125
	v_mov_b32_e32 v88, v125
	v_mov_b32_e32 v89, v125
	v_mov_b32_e32 v90, v125
	v_mov_b32_e32 v91, v125
	v_mov_b32_e32 v92, v125
	v_mov_b32_e32 v93, v125
	v_mov_b32_e32 v94, v125
	v_mov_b32_e32 v95, v125
	v_mov_b32_e32 v96, v125
	v_mov_b32_e32 v97, v125
	v_mov_b32_e32 v98, v125
	v_mov_b32_e32 v99, v125
	v_mov_b32_e32 v100, v125
	v_mov_b32_e32 v101, v125
	v_mov_b32_e32 v102, v125
	v_mov_b32_e32 v103, v125
	v_mov_b32_e32 v104, v125
	v_mov_b32_e32 v105, v125
	v_mov_b32_e32 v106, v125
	v_mov_b32_e32 v107, v125
	v_mov_b32_e32 v108, v125
	v_mov_b32_e32 v109, v125
	v_mov_b32_e32 v110, v125
	v_mov_b32_e32 v111, v125
	v_mov_b32_e32 v112, v125
	v_mov_b32_e32 v113, v125
	v_mov_b32_e32 v114, v125
	v_mov_b32_e32 v115, v125
	v_mov_b32_e32 v116, v125
	v_mov_b32_e32 v117, v125
	v_mov_b32_e32 v118, v125
	v_mov_b32_e32 v119, v125
	v_mov_b32_e32 v120, v125
	v_mov_b32_e32 v121, v125
	v_mov_b32_e32 v122, v125
	v_mov_b32_e32 v123, v125
	v_mov_b32_e32 v124, v125
	v_mov_b32_e32 v126, v125
	v_mov_b32_e32 v127, v125
	v_mov_b32_e32 v128, v125
	v_mov_b32_e32 v129, v125
	s_and_saveexec_b64 s[2:3], s[4:5]
	s_cbranch_execz .LBB0_398
	s_barrier
.LBB0_398:
	s_or_b64 exec, exec, s[2:3]
	s_add_u32 s2, s10, 0x80
	s_waitcnt vmcnt(4)
	s_barrier
	s_addc_u32 s3, s11, 0
	s_mov_b32 s75, m0
	s_mov_b32 m0, s78
	s_nop 0
	global_load_lds_dwordx4 v135, s[2:3]
	s_mov_b32 m0, s75
	s_mov_b32 s75, m0
	s_mov_b32 m0, s79
	s_nop 0
	global_load_lds_dwordx4 v182, s[2:3]
	s_mov_b32 m0, s75
	s_add_u32 s2, s12, 0x80
	s_addc_u32 s3, s13, 0
	s_mov_b32 s75, m0
	s_mov_b32 m0, s80
	s_nop 0
	global_load_lds_dwordx4 v135, s[2:3]
	s_mov_b32 m0, s75
	s_add_u32 s0, s0, 0x80
	s_mov_b32 s75, m0
	s_mov_b32 m0, s81
	s_nop 0
	global_load_lds_dwordx4 v182, s[2:3]
	s_mov_b32 m0, s75
	s_addc_u32 s1, s1, 0
	s_mov_b32 s2, m0
	s_mov_b32 m0, s82
	s_nop 0
	global_load_lds_dwordx4 v135, s[0:1]
	s_mov_b32 m0, s2
	s_andn2_b64 vcc, exec, s[20:21]
	s_mov_b32 s2, m0
	s_mov_b32 m0, s83
	s_nop 0
	global_load_lds_dwordx4 v182, s[0:1]
	s_mov_b32 m0, s2
	s_waitcnt vmcnt(6)
	s_barrier
	s_cbranch_vccnz .LBB0_402
	s_add_u32 s0, s91, 0x80
	s_addc_u32 s1, s76, 0
	s_mul_i32 s1, s54, s1
	s_mul_hi_u32 s2, s54, s0
	s_add_i32 s1, s2, s1
	s_mul_i32 s2, s55, s0
	s_add_i32 s1, s1, s2
	s_mul_i32 s0, s54, s0
	s_add_u32 s0, s56, s0
	s_addc_u32 s1, s57, s1
	s_add_u32 s2, s74, 0x80
	s_addc_u32 s3, s77, 0
	s_mul_i32 s3, s54, s3
	s_mul_hi_u32 s56, s54, s2
	s_add_i32 s3, s56, s3
	s_mul_i32 s56, s55, s2
	s_add_i32 s3, s3, s56
	s_mul_i32 s2, s54, s2
	s_add_u32 s2, s14, s2
	s_addc_u32 s3, s15, s3
	s_mov_b32 s56, 0
	s_mov_b64 s[14:15], 0
